# stack: mixer C VALU cuts + wait ladder merge, GEMM epilogue counted vmcnt, first seam uses XCD barrier, gate_up DMA loads via SGPR base
# speedup vs baseline: 1.0086x; 1.0034x over previous
; #define LAS __attribute__((address_space(3)))
; #define DIL_TILE(u, SH, T0) do { const int g_ = (u) < 10 ? 0 : ((u) < 14 ? 1 : 2); SH = 2 * g_; const int tt_ = (u) - (g_ == 0 ? 0 : (g_ == 1 ? 10 : 14)); T0 = tmin - (64 << SH) + ((64 * tt_) << SH); } while (0)
; #define DIL_LOADK(SH, T0) DIL_LOADX(SH, T0, lrow, kb, kr)
; #define DIL_LOADV(SH, T0) DIL_LOADX(SH, T0, lrowV, vb, vr)
; __global__ void __launch_bounds__(NTHREADS) fwd_megakernel(Params P) {
;     ...
;                 int sh, t0; DIL_TILE(ubeg, sh, t0); DIL_LOADK(sh, t0); DIL_LOADV(sh, t0);
;                 for (int u = ubeg; u < uend; ++u) {
;                     LAS unsigned char* kw = wl + ch * 1024 + (lrow ^ ch) * 16; LAS unsigned char* vw = wl + 8192 + dhV * 4096 + lrowV * 64 + cwV * 16; asm volatile("" : "+v"(kw), "+v"(vw));
; #pragma unroll
;                     for (int j = 0; j < 8; ++j) { *(LAS u32x4*)(kw + j * 128) = kr[j]; *(LAS u32x4*)(vw + j * 512) = vr[j]; }
;                     int tq_ = tq; asm volatile("" : "+v"(tq_));
;                     ModDil mod{(float)(tq_ - t0 - ((4 * hi) << sh)), (float)(1 << sh), (float)(64 << sh), slope2, (float)tq_, (float)(tq_ - S), (t0 >= 0) && (t0 + (63 << sh) < S)};
;                     bf16x8 pa[4];
;                     if (u + 1 < uend) { DIL_TILE(u + 1, sh, t0); DIL_LOADK(sh, t0); }
.LBB0_34:
	s_cmp_lt_u32 s20, s13
	s_cselect_b64 s[48:49], -1, 0
	s_cmp_ge_u32 s20, s13
	v_mov_b32_e32 v50, v235
	v_mov_b32_e32 v51, v234
	s_cselect_b64 s[50:51], -1, 0
	v_mov_b32_e32 v188, v170
	s_and_b64 vcc, exec, s[50:51]
	s_waitcnt vmcnt(8)
	ds_write_b128 v51, v[98:101]
	ds_write_b128 v51, v[102:105] offset:128
	ds_write_b128 v51, v[106:109] offset:256
	ds_write_b128 v51, v[110:113] offset:384
	ds_write_b128 v51, v[114:117] offset:512
	ds_write_b128 v51, v[118:121] offset:640
	ds_write_b128 v51, v[122:125] offset:768
	ds_write_b128 v51, v[126:129] offset:896
	s_waitcnt vmcnt(4)
	ds_write_b128 v50, v[130:133]
	ds_write_b128 v50, v[134:137] offset:512
	ds_write_b128 v50, v[138:141] offset:1024
	ds_write_b128 v50, v[142:145] offset:1536
	s_waitcnt vmcnt(0)
	ds_write_b128 v50, v[146:149] offset:2048
	ds_write_b128 v50, v[150:153] offset:2560
	ds_write_b128 v50, v[154:157] offset:3072
	ds_write_b128 v50, v[158:161] offset:3584
	s_cbranch_vccnz .LBB0_40
	s_add_i32 s0, s20, -1
	s_cmp_lt_u32 s0, 13
	s_cselect_b32 s2, 2, 4
	s_add_i32 s3, s20, -10
	s_cmp_lt_u32 s3, 4
	s_cselect_b32 s3, -10, -14
	s_cmp_gt_u32 s0, 8
	s_cselect_b32 s0, s3, 0
	s_cselect_b32 s41, s2, 0
	s_add_i32 s0, s0, s20
	s_lshl_b32 s2, s0, 6
	s_sub_i32 s54, s2, 64
	s_lshl_b32 s0, s54, s41
	s_add_i32 s0, s0, s16
	s_cmp_lt_i32 s0, 0
	s_cselect_b64 s[10:11], -1, 0
	v_mov_b32_e32 v50, v185
	s_and_b64 vcc, exec, s[10:11]
	s_cbranch_vccnz .LBB0_53
	s_add_i32 s2, s2, -1
	s_lshl_b32 s2, s2, s41
	s_add_i32 s10, s2, s16
	s_cmp_ge_i32 s10, s23
	s_mov_b64 s[2:3], -1
	s_cselect_b64 s[10:11], -1, 0
	v_add_u32_e32 v51, s54, v50
	s_andn2_b64 vcc, exec, s[10:11]
	v_lshlrev_b32_e32 v50, s41, v51
	s_cbranch_vccnz .LBB0_38

; #define PG8_STAGE(bufoff, gbase, voff) do { _Pragma("unroll") for (int _i = 0; _i < 2; ++_i) \
;         __builtin_amdgcn_global_load_lds((const unsigned*)((const char*)(gbase) + (voff)[_i]), (LAS unsigned*)(lds + (bufoff) + ldsw + _i * 8192), 16, 0, 0); } while (0)
; #define PG8_LDA(dst, b, h) do { _Pragma("unroll") for (int m = 0; m < 4; ++m) _Pragma("unroll") for (int k = 0; k < 2; ++k) dst[m][k] = *(const LAS bf16x8*)(lds + PG8_SA(b, h) + aoff + m * 2048 + k * 1024); } while (0)
; #define PG8_LDB(dst, b, h) do { _Pragma("unroll") for (int n = 0; n < 2; ++n) _Pragma("unroll") for (int k = 0; k < 2; ++k) dst[n][k] = *(const LAS bf16x8*)(lds + PG8_SB(b, h) + boff + n * 2048 + k * 1024); } while (0)
; #define PG8_MMA(ai, bj, At, Bt) do { __builtin_amdgcn_s_setprio(1); _Pragma("unroll") for (int m = 0; m < 4; ++m) _Pragma("unroll") for (int n = 0; n < 2; ++n) _Pragma("unroll") for (int k = 0; k < 2; ++k) \
;         acc[ai][bj][m][n] = __builtin_amdgcn_mfma_f32_16x16x32_bf16(Bt[n][k], At[m][k], acc[ai][bj][m][n], 0, 0, 0); __builtin_amdgcn_s_setprio(0); } while (0)
; #define PG8_WAIT_V(n) asm volatile("s_waitcnt vmcnt(" #n ")" ::: "memory")
; #define PG8_WAIT_L(n) asm volatile("s_waitcnt lgkmcnt(" #n ")" ::: "memory")
; #define PG8_BAR __builtin_amdgcn_s_barrier()
; #define PG8_SCHED __builtin_amdgcn_sched_barrier(0)
; template <class Epi>
; __device__ __forceinline__ void gemm_phase(LAS unsigned char* lds, const Gemm g, const StaticOrder& S, const Epi& E, const int wave_id) {
;     ...
;             PG8_LDB(B0, 0, 0); PG8_LDB(B1, 0, 1); PG8_SCHED; PG8_LDA(At, 0, 0); PG8_STAGE(PG8_SA(1, 1), a1 + hstep, voffA);
;             PG8_WAIT_V(8); PG8_WAIT_L(0); PG8_BAR; PG8_MMA(0, 0, At, B0); PG8_MMA(0, 1, At, B1); PG8_BAR; PG8_SCHED;
;             PG8_LDA(At, 0, 1); PG8_STAGE(PG8_SB(0, 0), b2, voffB); PG8_STAGE(PG8_SB(0, 1), b2 + hstep, voffB); PG8_STAGE(PG8_SA(0, 0), a2, voffA);
;             PG8_WAIT_V(8); PG8_WAIT_L(0); PG8_BAR; PG8_MMA(1, 0, At, B0); PG8_MMA(1, 1, At, B1); PG8_BAR; PG8_SCHED;
.LBB0_146:
	s_add_u32 s33, s42, 0xfffc0080
	s_addc_u32 s35, s43, -1
	s_and_b64 s[44:45], s[10:11], exec
	s_cselect_b32 s45, s2, s35
	s_cselect_b32 s44, s3, s33
	s_add_i32 s33, 0, 0x10000
	s_and_b64 s[10:11], s[10:11], exec
	v_add_u32_e32 v141, s33, v145
	s_cselect_b32 s11, s19, s22
	s_cselect_b32 s10, s20, s21
	s_add_i32 s35, 0, 0x14000
	ds_read_b128 v[156:159], v141
	ds_read_b128 v[164:167], v141 offset:1024
	ds_read_b128 v[168:171], v141 offset:2048
	ds_read_b128 v[172:175], v141 offset:3072
	v_add_u32_e32 v141, s35, v145
	ds_read_b128 v[186:189], v141
	ds_read_b128 v[190:193], v141 offset:1024
	ds_read_b128 v[194:197], v141 offset:2048
	ds_read_b128 v[198:201], v141 offset:3072
	s_add_i32 m0, s6, 0xc000
	ds_read_b128 v[202:205], v147
	ds_read_b128 v[206:209], v147 offset:1024
	ds_read_b128 v[210:213], v147 offset:2048
	ds_read_b128 v[214:217], v147 offset:3072
	ds_read_b128 v[234:237], v147 offset:4096
	ds_read_b128 v[238:241], v147 offset:5120
	ds_read_b128 v[242:245], v147 offset:6144
	ds_read_b128 v[246:249], v147 offset:7168
	global_load_lds_dwordx4 v136, s[42:43]
	s_add_i32 m0, s6, 0xe000
	s_nop 0
	global_load_lds_dwordx4 v138, s[42:43]
	s_waitcnt vmcnt(8)
	s_waitcnt lgkmcnt(0)
	s_barrier
	s_setprio 1
	s_waitcnt lgkmcnt(0)
	v_mfma_f32_16x16x32_bf16 v[126:129], v[156:159], v[202:205], v[126:129]
	v_mfma_f32_16x16x32_bf16 v[122:125], v[168:171], v[202:205], v[122:125]
	v_mfma_f32_16x16x32_bf16 v[110:113], v[156:159], v[210:213], v[110:113]
	v_mfma_f32_16x16x32_bf16 v[106:109], v[168:171], v[210:213], v[106:109]
	v_mfma_f32_16x16x32_bf16 v[94:97], v[156:159], v[234:237], v[94:97]
	v_mfma_f32_16x16x32_bf16 v[90:93], v[168:171], v[234:237], v[90:93]
	v_mfma_f32_16x16x32_bf16 v[78:81], v[156:159], v[242:245], v[78:81]
	v_mfma_f32_16x16x32_bf16 v[74:77], v[168:171], v[242:245], v[74:77]
	v_mfma_f32_16x16x32_bf16 v[126:129], v[164:167], v[206:209], v[126:129]
	v_mfma_f32_16x16x32_bf16 v[122:125], v[172:175], v[206:209], v[122:125]
	v_mfma_f32_16x16x32_bf16 v[110:113], v[164:167], v[214:217], v[110:113]
	v_mfma_f32_16x16x32_bf16 v[106:109], v[172:175], v[214:217], v[106:109]
	v_mfma_f32_16x16x32_bf16 v[94:97], v[164:167], v[238:241], v[94:97]
	v_mfma_f32_16x16x32_bf16 v[90:93], v[172:175], v[238:241], v[90:93]
	v_mfma_f32_16x16x32_bf16 v[78:81], v[164:167], v[246:249], v[78:81]
	v_mfma_f32_16x16x32_bf16 v[74:77], v[172:175], v[246:249], v[74:77]
	s_setprio 0
	s_setprio 1
	v_mfma_f32_16x16x32_bf16 v[118:121], v[186:189], v[202:205], v[118:121]
	v_mfma_f32_16x16x32_bf16 v[114:117], v[194:197], v[202:205], v[114:117]
	v_mfma_f32_16x16x32_bf16 v[102:105], v[186:189], v[210:213], v[102:105]
	v_mfma_f32_16x16x32_bf16 v[98:101], v[194:197], v[210:213], v[98:101]
	v_mfma_f32_16x16x32_bf16 v[86:89], v[186:189], v[234:237], v[86:89]
	v_mfma_f32_16x16x32_bf16 v[82:85], v[194:197], v[234:237], v[82:85]
	v_mfma_f32_16x16x32_bf16 v[70:73], v[186:189], v[242:245], v[70:73]
	v_mfma_f32_16x16x32_bf16 v[66:69], v[194:197], v[242:245], v[66:69]
	v_mfma_f32_16x16x32_bf16 v[118:121], v[190:193], v[206:209], v[118:121]
	v_mfma_f32_16x16x32_bf16 v[114:117], v[198:201], v[206:209], v[114:117]
	v_mfma_f32_16x16x32_bf16 v[102:105], v[190:193], v[214:217], v[102:105]
	v_mfma_f32_16x16x32_bf16 v[98:101], v[198:201], v[214:217], v[98:101]
	v_mfma_f32_16x16x32_bf16 v[86:89], v[190:193], v[238:241], v[86:89]
	v_mfma_f32_16x16x32_bf16 v[82:85], v[198:201], v[238:241], v[82:85]
	v_mfma_f32_16x16x32_bf16 v[70:73], v[190:193], v[246:249], v[70:73]
	v_mfma_f32_16x16x32_bf16 v[66:69], v[198:201], v[246:249], v[66:69]
	s_setprio 0
	s_barrier
	s_add_i32 s33, s33, s4
	s_mov_b32 m0, s33
	ds_read_b128 v[202:205], v147 offset:16384
	ds_read_b128 v[206:209], v147 offset:17408
	ds_read_b128 v[210:213], v147 offset:18432
	ds_read_b128 v[214:217], v147 offset:19456
	ds_read_b128 v[234:237], v147 offset:20480
	ds_read_b128 v[238:241], v147 offset:21504
	ds_read_b128 v[242:245], v147 offset:22528
	ds_read_b128 v[246:249], v147 offset:23552
	global_load_lds_dwordx4 v0, s[10:11]
	s_add_i32 m0, s33, 0x2000
	s_add_u32 s46, s10, 0x40000
	s_addc_u32 s47, s11, 0
	s_add_i32 s33, s35, s4
	global_load_lds_dwordx4 v130, s[10:11]
	s_mov_b32 m0, s33
	s_nop 0
	global_load_lds_dwordx4 v0, s[46:47]
	s_add_i32 m0, s33, 0x2000
	s_nop 0
	global_load_lds_dwordx4 v130, s[46:47]
	s_mov_b32 m0, s6
	s_nop 0
	global_load_lds_dwordx4 v134, s[44:45]
	s_mov_b32 m0, s7
	s_nop 0
	global_load_lds_dwordx4 v132, s[44:45]
	s_waitcnt vmcnt(8)
	s_waitcnt lgkmcnt(0)
	s_barrier
	s_setprio 1
	s_waitcnt lgkmcnt(0)
	v_mfma_f32_16x16x32_bf16 v[62:65], v[156:159], v[202:205], v[62:65]
	v_mfma_f32_16x16x32_bf16 v[58:61], v[168:171], v[202:205], v[58:61]
	v_mfma_f32_16x16x32_bf16 v[46:49], v[156:159], v[210:213], v[46:49]
	v_mfma_f32_16x16x32_bf16 v[42:45], v[168:171], v[210:213], v[42:45]
	v_mfma_f32_16x16x32_bf16 v[30:33], v[156:159], v[234:237], v[30:33]
	v_mfma_f32_16x16x32_bf16 v[26:29], v[168:171], v[234:237], v[26:29]
	v_mfma_f32_16x16x32_bf16 v[14:17], v[156:159], v[242:245], v[14:17]
	v_mfma_f32_16x16x32_bf16 v[10:13], v[168:171], v[242:245], v[10:13]
	v_mfma_f32_16x16x32_bf16 v[62:65], v[164:167], v[206:209], v[62:65]
	v_mfma_f32_16x16x32_bf16 v[58:61], v[172:175], v[206:209], v[58:61]
	v_mfma_f32_16x16x32_bf16 v[46:49], v[164:167], v[214:217], v[46:49]
	v_mfma_f32_16x16x32_bf16 v[42:45], v[172:175], v[214:217], v[42:45]
	v_mfma_f32_16x16x32_bf16 v[30:33], v[164:167], v[238:241], v[30:33]
	v_mfma_f32_16x16x32_bf16 v[26:29], v[172:175], v[238:241], v[26:29]
	v_mfma_f32_16x16x32_bf16 v[14:17], v[164:167], v[246:249], v[14:17]
	v_mfma_f32_16x16x32_bf16 v[10:13], v[172:175], v[246:249], v[10:13]
	s_setprio 0
	s_setprio 1
	v_mfma_f32_16x16x32_bf16 v[54:57], v[186:189], v[202:205], v[54:57]
	v_mfma_f32_16x16x32_bf16 v[50:53], v[194:197], v[202:205], v[50:53]
	v_mfma_f32_16x16x32_bf16 v[38:41], v[186:189], v[210:213], v[38:41]
	v_mfma_f32_16x16x32_bf16 v[34:37], v[194:197], v[210:213], v[34:37]
	v_mfma_f32_16x16x32_bf16 v[22:25], v[186:189], v[234:237], v[22:25]
	v_mfma_f32_16x16x32_bf16 v[18:21], v[194:197], v[234:237], v[18:21]
	v_mfma_f32_16x16x32_bf16 v[6:9], v[186:189], v[242:245], v[6:9]
	v_mfma_f32_16x16x32_bf16 v[2:5], v[194:197], v[242:245], v[2:5]
	v_mfma_f32_16x16x32_bf16 v[54:57], v[190:193], v[206:209], v[54:57]
	v_mfma_f32_16x16x32_bf16 v[50:53], v[198:201], v[206:209], v[50:53]
	v_mfma_f32_16x16x32_bf16 v[38:41], v[190:193], v[214:217], v[38:41]
	v_mfma_f32_16x16x32_bf16 v[34:37], v[198:201], v[214:217], v[34:37]
	v_mfma_f32_16x16x32_bf16 v[22:25], v[190:193], v[238:241], v[22:25]
	v_mfma_f32_16x16x32_bf16 v[18:21], v[198:201], v[238:241], v[18:21]
	v_mfma_f32_16x16x32_bf16 v[6:9], v[190:193], v[246:249], v[6:9]
	v_mfma_f32_16x16x32_bf16 v[2:5], v[198:201], v[246:249], v[2:5]
	s_setprio 0
	s_barrier
; #define PG8_STAGE(bufoff, gbase, voff) do { _Pragma("unroll") for (int _i = 0; _i < 2; ++_i) \
;         __builtin_amdgcn_global_load_lds((const unsigned*)((const char*)(gbase) + (voff)[_i]), (LAS unsigned*)(lds + (bufoff) + ldsw + _i * 8192), 16, 0, 0); } while (0)
; #define PG8_LDA(dst, b, h) do { _Pragma("unroll") for (int m = 0; m < 4; ++m) _Pragma("unroll") for (int k = 0; k < 2; ++k) dst[m][k] = *(const LAS bf16x8*)(lds + PG8_SA(b, h) + aoff + m * 2048 + k * 1024); } while (0)
; #define PG8_LDB(dst, b, h) do { _Pragma("unroll") for (int n = 0; n < 2; ++n) _Pragma("unroll") for (int k = 0; k < 2; ++k) dst[n][k] = *(const LAS bf16x8*)(lds + PG8_SB(b, h) + boff + n * 2048 + k * 1024); } while (0)
; #define PG8_MMA(ai, bj, At, Bt) do { __builtin_amdgcn_s_setprio(1); _Pragma("unroll") for (int m = 0; m < 4; ++m) _Pragma("unroll") for (int n = 0; n < 2; ++n) _Pragma("unroll") for (int k = 0; k < 2; ++k) \
;         acc[ai][bj][m][n] = __builtin_amdgcn_mfma_f32_16x16x32_bf16(Bt[n][k], At[m][k], acc[ai][bj][m][n], 0, 0, 0); __builtin_amdgcn_s_setprio(0); } while (0)
; #define PG8_WAIT_V(n) asm volatile("s_waitcnt vmcnt(" #n ")" ::: "memory")
; #define PG8_WAIT_L(n) asm volatile("s_waitcnt lgkmcnt(" #n ")" ::: "memory")
; #define PG8_BAR __builtin_amdgcn_s_barrier()
; #define PG8_SCHED __builtin_amdgcn_sched_barrier(0)
; template <class Epi>
; __device__ __forceinline__ void gemm_phase(LAS unsigned char* lds, const Gemm g, const StaticOrder& S, const Epi& E, const int wave_id) {
;     ...
;         for (int t = 0; t < nt; t += 2) {
;             const bool last = (t == nt - 2);
;             if (last) E.pre(cur, wr, fr, epre);
;             const char* a1 = cA + (size_t)(t + 1) * kstep;
;             const char* a2 = last ? nA : cA + (size_t)(t + 2) * kstep; const char* b2 = last ? nB : cB + (size_t)(t + 2) * kstep;
;     ...
;             PG8_LDB(B0, 1, 0); PG8_LDB(B1, 1, 1); PG8_SCHED; PG8_LDA(At, 1, 0); PG8_STAGE(PG8_SA(0, 1), a2 + hstep, voffA);
;             PG8_WAIT_V(8); PG8_WAIT_L(0); PG8_BAR; PG8_MMA(0, 0, At, B0); PG8_MMA(0, 1, At, B1); PG8_BAR; PG8_SCHED;
;             PG8_LDA(At, 1, 1); PG8_STAGE(PG8_SB(1, 0), b3, voffB); PG8_STAGE(PG8_SB(1, 1), b3 + hstep, voffB); PG8_STAGE(PG8_SA(1, 0), a3, voffA);
;             PG8_WAIT_V(8); PG8_WAIT_L(0); PG8_BAR; PG8_MMA(1, 0, At, B0); PG8_MMA(1, 1, At, B1); PG8_BAR; PG8_SCHED;
	s_add_i32 s33, 0, 0x18000
	v_add_u32_e32 v141, s33, v145
	s_add_i32 s35, 0, 0x1c000
	ds_read_b128 v[156:159], v141
	ds_read_b128 v[164:167], v141 offset:1024
	ds_read_b128 v[168:171], v141 offset:2048
	ds_read_b128 v[172:175], v141 offset:3072
	v_add_u32_e32 v141, s35, v145
	ds_read_b128 v[186:189], v141
	ds_read_b128 v[190:193], v141 offset:1024
	ds_read_b128 v[194:197], v141 offset:2048
	ds_read_b128 v[198:201], v141 offset:3072
	s_add_u32 s46, s44, 0x40000
	s_addc_u32 s47, s45, 0
	s_mov_b32 m0, s8
	ds_read_b128 v[202:205], v147 offset:32768
	ds_read_b128 v[206:209], v147 offset:33792
	ds_read_b128 v[210:213], v147 offset:34816
	ds_read_b128 v[214:217], v147 offset:35840
	ds_read_b128 v[234:237], v147 offset:36864
	ds_read_b128 v[238:241], v147 offset:37888
	ds_read_b128 v[242:245], v147 offset:38912
	ds_read_b128 v[246:249], v147 offset:39936
	global_load_lds_dwordx4 v134, s[46:47]
	s_mov_b32 m0, s9
	s_nop 0
	global_load_lds_dwordx4 v132, s[46:47]
	s_waitcnt vmcnt(8)
	s_waitcnt lgkmcnt(0)
	s_barrier
	s_setprio 1
	s_waitcnt lgkmcnt(0)
	v_mfma_f32_16x16x32_bf16 v[126:129], v[156:159], v[202:205], v[126:129]
	v_mfma_f32_16x16x32_bf16 v[122:125], v[168:171], v[202:205], v[122:125]
	v_mfma_f32_16x16x32_bf16 v[110:113], v[156:159], v[210:213], v[110:113]
	v_mfma_f32_16x16x32_bf16 v[106:109], v[168:171], v[210:213], v[106:109]
	v_mfma_f32_16x16x32_bf16 v[94:97], v[156:159], v[234:237], v[94:97]
	v_mfma_f32_16x16x32_bf16 v[90:93], v[168:171], v[234:237], v[90:93]
	v_mfma_f32_16x16x32_bf16 v[78:81], v[156:159], v[242:245], v[78:81]
	v_mfma_f32_16x16x32_bf16 v[74:77], v[168:171], v[242:245], v[74:77]
	v_mfma_f32_16x16x32_bf16 v[126:129], v[164:167], v[206:209], v[126:129]
	v_mfma_f32_16x16x32_bf16 v[122:125], v[172:175], v[206:209], v[122:125]
	v_mfma_f32_16x16x32_bf16 v[110:113], v[164:167], v[214:217], v[110:113]
	v_mfma_f32_16x16x32_bf16 v[106:109], v[172:175], v[214:217], v[106:109]
	v_mfma_f32_16x16x32_bf16 v[94:97], v[164:167], v[238:241], v[94:97]
	v_mfma_f32_16x16x32_bf16 v[90:93], v[172:175], v[238:241], v[90:93]
	v_mfma_f32_16x16x32_bf16 v[78:81], v[164:167], v[246:249], v[78:81]
	v_mfma_f32_16x16x32_bf16 v[74:77], v[172:175], v[246:249], v[74:77]
	s_setprio 0
	s_setprio 1
	v_mfma_f32_16x16x32_bf16 v[118:121], v[186:189], v[202:205], v[118:121]
	v_mfma_f32_16x16x32_bf16 v[114:117], v[194:197], v[202:205], v[114:117]
	v_mfma_f32_16x16x32_bf16 v[102:105], v[186:189], v[210:213], v[102:105]
	v_mfma_f32_16x16x32_bf16 v[98:101], v[194:197], v[210:213], v[98:101]
	v_mfma_f32_16x16x32_bf16 v[86:89], v[186:189], v[234:237], v[86:89]
	v_mfma_f32_16x16x32_bf16 v[82:85], v[194:197], v[234:237], v[82:85]
	v_mfma_f32_16x16x32_bf16 v[70:73], v[186:189], v[242:245], v[70:73]
	v_mfma_f32_16x16x32_bf16 v[66:69], v[194:197], v[242:245], v[66:69]
	v_mfma_f32_16x16x32_bf16 v[118:121], v[190:193], v[206:209], v[118:121]
	v_mfma_f32_16x16x32_bf16 v[114:117], v[198:201], v[206:209], v[114:117]
	v_mfma_f32_16x16x32_bf16 v[102:105], v[190:193], v[214:217], v[102:105]
	v_mfma_f32_16x16x32_bf16 v[98:101], v[198:201], v[214:217], v[98:101]
	v_mfma_f32_16x16x32_bf16 v[86:89], v[190:193], v[238:241], v[86:89]
	v_mfma_f32_16x16x32_bf16 v[82:85], v[198:201], v[238:241], v[82:85]
	v_mfma_f32_16x16x32_bf16 v[70:73], v[190:193], v[246:249], v[70:73]
	v_mfma_f32_16x16x32_bf16 v[66:69], v[198:201], v[246:249], v[66:69]
	s_setprio 0
	s_barrier
	s_add_i32 s33, s33, s4
	s_add_u32 s46, s10, 0x80
	s_addc_u32 s47, s11, 0
	s_mov_b32 m0, s33
	ds_read_b128 v[202:205], v147 offset:49152
	ds_read_b128 v[206:209], v147 offset:50176
	ds_read_b128 v[210:213], v147 offset:51200
	ds_read_b128 v[214:217], v147 offset:52224
	ds_read_b128 v[234:237], v147 offset:53248
	ds_read_b128 v[238:241], v147 offset:54272
	ds_read_b128 v[242:245], v147 offset:55296
	ds_read_b128 v[246:249], v147 offset:56320
	global_load_lds_dwordx4 v0, s[46:47]
	s_add_i32 m0, s33, 0x2000
	s_add_i32 s33, s35, s4
	global_load_lds_dwordx4 v130, s[46:47]
	s_add_u32 s10, s10, 0x40080
	s_addc_u32 s11, s11, 0
	s_mov_b32 m0, s33
	s_nop 0
	global_load_lds_dwordx4 v0, s[10:11]
	s_add_i32 m0, s33, 0x2000
	s_nop 0
	global_load_lds_dwordx4 v130, s[10:11]
	s_add_u32 s46, s44, 0x80
	s_addc_u32 s47, s45, 0
	s_mov_b32 m0, s16
	s_nop 0
	global_load_lds_dwordx4 v134, s[46:47]
	s_mov_b32 m0, s17
	s_nop 0
	global_load_lds_dwordx4 v132, s[46:47]
	s_waitcnt vmcnt(8)
	s_waitcnt lgkmcnt(0)
	s_barrier
	s_setprio 1
	s_waitcnt lgkmcnt(0)
	v_mfma_f32_16x16x32_bf16 v[62:65], v[156:159], v[202:205], v[62:65]
	v_mfma_f32_16x16x32_bf16 v[58:61], v[168:171], v[202:205], v[58:61]
	v_mfma_f32_16x16x32_bf16 v[46:49], v[156:159], v[210:213], v[46:49]
	v_mfma_f32_16x16x32_bf16 v[42:45], v[168:171], v[210:213], v[42:45]
	v_mfma_f32_16x16x32_bf16 v[30:33], v[156:159], v[234:237], v[30:33]
	v_mfma_f32_16x16x32_bf16 v[26:29], v[168:171], v[234:237], v[26:29]
	v_mfma_f32_16x16x32_bf16 v[14:17], v[156:159], v[242:245], v[14:17]
	v_mfma_f32_16x16x32_bf16 v[10:13], v[168:171], v[242:245], v[10:13]
	v_mfma_f32_16x16x32_bf16 v[62:65], v[164:167], v[206:209], v[62:65]
	v_mfma_f32_16x16x32_bf16 v[58:61], v[172:175], v[206:209], v[58:61]
	v_mfma_f32_16x16x32_bf16 v[46:49], v[164:167], v[214:217], v[46:49]
	v_mfma_f32_16x16x32_bf16 v[42:45], v[172:175], v[214:217], v[42:45]
	v_mfma_f32_16x16x32_bf16 v[30:33], v[164:167], v[238:241], v[30:33]
	v_mfma_f32_16x16x32_bf16 v[26:29], v[172:175], v[238:241], v[26:29]
	v_mfma_f32_16x16x32_bf16 v[14:17], v[164:167], v[246:249], v[14:17]
	v_mfma_f32_16x16x32_bf16 v[10:13], v[172:175], v[246:249], v[10:13]
	s_setprio 0
	s_setprio 1
	v_mfma_f32_16x16x32_bf16 v[54:57], v[186:189], v[202:205], v[54:57]
	v_mfma_f32_16x16x32_bf16 v[50:53], v[194:197], v[202:205], v[50:53]
	v_mfma_f32_16x16x32_bf16 v[38:41], v[186:189], v[210:213], v[38:41]
	v_mfma_f32_16x16x32_bf16 v[34:37], v[194:197], v[210:213], v[34:37]
	v_mfma_f32_16x16x32_bf16 v[22:25], v[186:189], v[234:237], v[22:25]
	v_mfma_f32_16x16x32_bf16 v[18:21], v[194:197], v[234:237], v[18:21]
	v_mfma_f32_16x16x32_bf16 v[6:9], v[186:189], v[242:245], v[6:9]
	v_mfma_f32_16x16x32_bf16 v[2:5], v[194:197], v[242:245], v[2:5]
	v_mfma_f32_16x16x32_bf16 v[54:57], v[190:193], v[206:209], v[54:57]
	v_mfma_f32_16x16x32_bf16 v[50:53], v[198:201], v[206:209], v[50:53]
	v_mfma_f32_16x16x32_bf16 v[38:41], v[190:193], v[214:217], v[38:41]
	v_mfma_f32_16x16x32_bf16 v[34:37], v[198:201], v[214:217], v[34:37]
	v_mfma_f32_16x16x32_bf16 v[22:25], v[190:193], v[238:241], v[22:25]
	v_mfma_f32_16x16x32_bf16 v[18:21], v[198:201], v[238:241], v[18:21]
	v_mfma_f32_16x16x32_bf16 v[6:9], v[190:193], v[246:249], v[6:9]
	v_mfma_f32_16x16x32_bf16 v[2:5], v[198:201], v[246:249], v[2:5]
	s_setprio 0
	s_barrier
	s_add_i32 s31, s31, 2
	s_add_u32 s42, s42, 0x100
	s_addc_u32 s43, s43, 0
	s_add_u32 s21, s21, 0x100
	s_addc_u32 s22, s22, 0
	s_cmp_gt_u32 s31, 13
	s_cbranch_scc1 .LBB0_149

; __device__ __forceinline__ unsigned cvtpk(float lo, float hi) { f32x2 v = {lo, hi}; bf16x2_t b = __builtin_convertvector(v, bf16x2_t); return __builtin_bit_cast(unsigned, b); }
;     __device__ __forceinline__ void operator()(const f32x4 (&acc)[2][2][4][2], const Unit& u, int wr, int wc, int fr, int fq, const float (&pv)[8]) const {
;         const int row0 = u.pm * BM + wr * 64 + fr, col0 = u.pn * HALF + wc * 32 + 8 * fq;
; #pragma unroll
;         for (int ai = 0; ai < 2; ++ai)
; #pragma unroll
;             for (int m = 0; m < 4; ++m) { const int row = row0 + ai * HALF + m * 16; const float rs = __builtin_amdgcn_rsqf(pv[ai * 4 + m] * (1.f / DM) + EPS);
;                 float hv[8];
; #pragma unroll
;                 for (int n = 0; n < 2; ++n)
; #pragma unroll
;                     for (int j = 0; j < 4; ++j) { const float g = acc[ai][0][m][n][j] * rs, uu = acc[ai][1][m][n][j] * rs;
;                         const float e = __builtin_amdgcn_exp2f(-g * LOG2E); hv[n * 4 + j] = g * uu * __builtin_amdgcn_rcpf(1.f + e); }
;                 u32x4 w; w.x = cvtpk(hv[0], hv[1]); w.y = cvtpk(hv[2], hv[3]); w.z = cvtpk(hv[4], hv[5]); w.w = cvtpk(hv[6], hv[7]);
;                 *(u32x4*)(H + (size_t)row * DFF + col0) = w; }
;     }
.LBB0_151:
	s_waitcnt vmcnt(8)
	v_fmamk_f32 v141, v148, 0x3a800000, v222
	v_rsq_f32_e32 v142, v141
	v_lshl_or_b32 v156, s18, 7, v146
	v_ashrrev_i32_e32 v157, 31, v156
	s_movk_i32 s10, 0x1600
	v_pk_mul_f32 v[126:127], v[142:143], v[126:127] op_sel_hi:[0,1]
	v_pk_mul_f32 v[118:119], v[142:143], v[118:119] op_sel_hi:[0,1]
	v_mul_f32_e32 v143, 0xbfb8aa3b, v127
	v_mul_f32_e32 v141, 0xbfb8aa3b, v126
	v_exp_f32_e32 v143, v143
	v_exp_f32_e32 v141, v141
	v_pk_mul_f32 v[118:119], v[126:127], v[118:119]
	s_andn2_b64 vcc, exec, s[40:41]
	v_pk_mul_f32 v[128:129], v[142:143], v[128:129] op_sel_hi:[0,1]
	v_add_f32_e32 v126, 1.0, v141
	v_add_f32_e32 v127, 1.0, v143
	v_mul_f32_e32 v141, 0xbfb8aa3b, v128
	v_mul_f32_e32 v143, 0xbfb8aa3b, v129
	v_rcp_f32_e32 v126, v126
	v_rcp_f32_e32 v127, v127
	v_exp_f32_e32 v141, v141
	v_exp_f32_e32 v143, v143
	v_pk_mul_f32 v[118:119], v[126:127], v[118:119]
	v_add_f32_e32 v126, 1.0, v141
	v_add_f32_e32 v127, 1.0, v143
	v_rcp_f32_e32 v126, v126
	v_rcp_f32_e32 v127, v127
	v_pk_mul_f32 v[120:121], v[142:143], v[120:121] op_sel_hi:[0,1]
	v_pk_mul_f32 v[122:123], v[142:143], v[122:123] op_sel_hi:[0,1]
	v_pk_mul_f32 v[120:121], v[128:129], v[120:121]
	v_pk_mul_f32 v[114:115], v[142:143], v[114:115] op_sel_hi:[0,1]
	v_mul_f32_e32 v141, 0xbfb8aa3b, v122
	v_pk_mul_f32 v[120:121], v[126:127], v[120:121]
	v_mul_f32_e32 v127, 0xbfb8aa3b, v123
	v_pk_mul_f32 v[114:115], v[122:123], v[114:115]
	v_pk_mul_f32 v[122:123], v[142:143], v[124:125] op_sel_hi:[0,1]
	v_exp_f32_e32 v141, v141
	v_exp_f32_e32 v127, v127
	v_mul_f32_e32 v124, 0xbfb8aa3b, v122
	v_mul_f32_e32 v125, 0xbfb8aa3b, v123
	v_exp_f32_e32 v124, v124
	v_exp_f32_e32 v125, v125
	v_add_f32_e32 v126, 1.0, v141
	v_add_f32_e32 v127, 1.0, v127
	v_rcp_f32_e32 v126, v126
	v_rcp_f32_e32 v127, v127
	v_add_f32_e32 v124, 1.0, v124
	v_add_f32_e32 v125, 1.0, v125
	v_rcp_f32_e32 v124, v124
	v_rcp_f32_e32 v125, v125
	v_pk_mul_f32 v[116:117], v[142:143], v[116:117] op_sel_hi:[0,1]
	v_pk_mul_f32 v[114:115], v[126:127], v[114:115]
	v_pk_mul_f32 v[116:117], v[122:123], v[116:117]
	s_nop 0
	v_pk_mul_f32 v[122:123], v[124:125], v[116:117]
	v_cvt_pk_bf16_f32 v116, v118, v119
	v_cvt_pk_bf16_f32 v118, v114, v115
	v_fmamk_f32 v114, v149, 0x3a800000, v222
	v_cvt_pk_bf16_f32 v117, v120, v121
	v_rsq_f32_e32 v120, v114
	v_mov_b64_e32 v[114:115], s[14:15]
	v_cvt_pk_bf16_f32 v119, v122, v123
	v_mad_i64_i32 v[122:123], s[2:3], v140, s10, v[114:115]
	v_pk_mul_f32 v[124:125], v[120:121], v[110:111] op_sel_hi:[0,1]
	v_mul_f32_e32 v110, 0xbfb8aa3b, v124
	v_exp_f32_e32 v121, v110
	v_lshlrev_b64 v[110:111], 1, v[156:157]
	v_lshl_add_u64 v[122:123], v[122:123], 0, v[110:111]
	global_store_dwordx4 v[122:123], v[116:119], off
	v_pk_mul_f32 v[112:113], v[120:121], v[112:113] op_sel_hi:[0,1]
	v_pk_mul_f32 v[102:103], v[120:121], v[102:103] op_sel_hi:[0,1]
	v_mul_f32_e32 v117, 0xbfb8aa3b, v125
	v_exp_f32_e32 v117, v117
	v_add_f32_e32 v116, 1.0, v121
	v_mul_f32_e32 v118, 0xbfb8aa3b, v112
	v_rcp_f32_e32 v116, v116
	v_add_f32_e32 v117, 1.0, v117
	v_rcp_f32_e32 v117, v117
	v_exp_f32_e32 v118, v118
	v_pk_mul_f32 v[102:103], v[124:125], v[102:103]
	v_pk_mul_f32 v[106:107], v[120:121], v[106:107] op_sel_hi:[0,1]
	v_pk_mul_f32 v[104:105], v[120:121], v[104:105] op_sel_hi:[0,1]
	v_mul_f32_e32 v119, 0xbfb8aa3b, v113
	v_pk_mul_f32 v[102:103], v[116:117], v[102:103]
	v_add_f32_e32 v116, 1.0, v118
	v_mul_f32_e32 v118, 0xbfb8aa3b, v106
	v_pk_mul_f32 v[104:105], v[112:113], v[104:105]
	v_mul_f32_e32 v113, 0xbfb8aa3b, v107
	v_pk_mul_f32 v[98:99], v[120:121], v[98:99] op_sel_hi:[0,1]
	v_exp_f32_e32 v118, v118
	v_exp_f32_e32 v113, v113
	v_pk_mul_f32 v[98:99], v[106:107], v[98:99]
	v_pk_mul_f32 v[106:107], v[120:121], v[108:109] op_sel_hi:[0,1]
	v_mul_f32_e32 v108, 0xbfb8aa3b, v106
	v_mul_f32_e32 v109, 0xbfb8aa3b, v107
	v_exp_f32_e32 v108, v108
	v_exp_f32_e32 v109, v109
	v_add_f32_e32 v112, 1.0, v118
	v_add_f32_e32 v113, 1.0, v113
	v_rcp_f32_e32 v112, v112
	v_rcp_f32_e32 v113, v113
	v_exp_f32_e32 v119, v119
	v_add_f32_e32 v108, 1.0, v108
	v_add_f32_e32 v109, 1.0, v109
	v_rcp_f32_e32 v108, v108
	v_rcp_f32_e32 v109, v109
	v_pk_mul_f32 v[112:113], v[112:113], v[98:99]
	v_pk_mul_f32 v[98:99], v[120:121], v[100:101] op_sel_hi:[0,1]
	v_add_f32_e32 v117, 1.0, v119
	v_pk_mul_f32 v[98:99], v[106:107], v[98:99]
	v_rcp_f32_e32 v116, v116
	v_rcp_f32_e32 v117, v117
	v_pk_mul_f32 v[106:107], v[108:109], v[98:99]
	v_fmamk_f32 v99, v150, 0x3a800000, v222
	v_cvt_pk_bf16_f32 v98, v102, v103
	v_rsq_f32_e32 v102, v99
	v_pk_mul_f32 v[104:105], v[116:117], v[104:105]
	v_or_b32_e32 v108, 16, v140
	v_cvt_pk_bf16_f32 v99, v104, v105
	v_pk_mul_f32 v[94:95], v[102:103], v[94:95] op_sel_hi:[0,1]
	v_mad_i64_i32 v[104:105], s[2:3], v108, s10, v[114:115]
	v_cvt_pk_bf16_f32 v100, v112, v113
	v_cvt_pk_bf16_f32 v101, v106, v107
	v_mul_f32_e32 v103, 0xbfb8aa3b, v94
	v_lshl_add_u64 v[104:105], v[104:105], 0, v[110:111]
	v_exp_f32_e32 v103, v103
	global_store_dwordx4 v[104:105], v[98:101], off
	v_pk_mul_f32 v[86:87], v[102:103], v[86:87] op_sel_hi:[0,1]
	s_nop 0
	v_mul_f32_e32 v99, 0xbfb8aa3b, v95
	v_exp_f32_e32 v99, v99
	v_add_f32_e32 v98, 1.0, v103
	v_pk_mul_f32 v[86:87], v[94:95], v[86:87]
	v_rcp_f32_e32 v98, v98
	v_add_f32_e32 v94, 1.0, v99
	v_rcp_f32_e32 v99, v94
	v_pk_mul_f32 v[94:95], v[102:103], v[96:97] op_sel_hi:[0,1]
	v_pk_mul_f32 v[90:91], v[102:103], v[90:91] op_sel_hi:[0,1]
	v_pk_mul_f32 v[88:89], v[102:103], v[88:89] op_sel_hi:[0,1]
	v_mul_f32_e32 v97, 0xbfb8aa3b, v95
	v_pk_mul_f32 v[86:87], v[98:99], v[86:87]
	v_mul_f32_e32 v98, 0xbfb8aa3b, v90
	v_pk_mul_f32 v[88:89], v[94:95], v[88:89]
	v_mul_f32_e32 v95, 0xbfb8aa3b, v91
	v_pk_mul_f32 v[82:83], v[102:103], v[82:83] op_sel_hi:[0,1]
; __device__ __forceinline__ unsigned cvtpk(float lo, float hi) { f32x2 v = {lo, hi}; bf16x2_t b = __builtin_convertvector(v, bf16x2_t); return __builtin_bit_cast(unsigned, b); }
;     __device__ __forceinline__ void operator()(const f32x4 (&acc)[2][2][4][2], const Unit& u, int wr, int wc, int fr, int fq, const float (&pv)[8]) const {
;     ...
;             for (int m = 0; m < 4; ++m) { const int row = row0 + ai * HALF + m * 16; const float rs = __builtin_amdgcn_rsqf(pv[ai * 4 + m] * (1.f / DM) + EPS);
;                 float hv[8];
; #pragma unroll
;                 for (int n = 0; n < 2; ++n)
; #pragma unroll
;                     for (int j = 0; j < 4; ++j) { const float g = acc[ai][0][m][n][j] * rs, uu = acc[ai][1][m][n][j] * rs;
;                         const float e = __builtin_amdgcn_exp2f(-g * LOG2E); hv[n * 4 + j] = g * uu * __builtin_amdgcn_rcpf(1.f + e); }
;                 u32x4 w; w.x = cvtpk(hv[0], hv[1]); w.y = cvtpk(hv[2], hv[3]); w.z = cvtpk(hv[4], hv[5]); w.w = cvtpk(hv[6], hv[7]);
;                 *(u32x4*)(H + (size_t)row * DFF + col0) = w; }
	v_exp_f32_e32 v98, v98
	v_exp_f32_e32 v95, v95
	v_pk_mul_f32 v[82:83], v[90:91], v[82:83]
	v_pk_mul_f32 v[90:91], v[102:103], v[92:93] op_sel_hi:[0,1]
	v_mul_f32_e32 v92, 0xbfb8aa3b, v90
	v_mul_f32_e32 v93, 0xbfb8aa3b, v91
	v_exp_f32_e32 v92, v92
	v_exp_f32_e32 v93, v93
	v_mul_f32_e32 v96, 0xbfb8aa3b, v94
	v_add_f32_e32 v94, 1.0, v98
	v_add_f32_e32 v95, 1.0, v95
	v_rcp_f32_e32 v94, v94
	v_rcp_f32_e32 v95, v95
	v_exp_f32_e32 v96, v96
	v_exp_f32_e32 v97, v97
	v_add_f32_e32 v92, 1.0, v92
	v_add_f32_e32 v93, 1.0, v93
	v_rcp_f32_e32 v92, v92
	v_rcp_f32_e32 v93, v93
	v_pk_mul_f32 v[94:95], v[94:95], v[82:83]
	v_pk_mul_f32 v[82:83], v[102:103], v[84:85] op_sel_hi:[0,1]
	v_add_f32_e32 v96, 1.0, v96
	v_add_f32_e32 v97, 1.0, v97
	v_pk_mul_f32 v[82:83], v[90:91], v[82:83]
	v_rcp_f32_e32 v96, v96
	v_rcp_f32_e32 v97, v97
	v_pk_mul_f32 v[90:91], v[92:93], v[82:83]
	v_fmamk_f32 v83, v151, 0x3a800000, v222
	v_cvt_pk_bf16_f32 v82, v86, v87
	v_rsq_f32_e32 v86, v83
	v_pk_mul_f32 v[88:89], v[96:97], v[88:89]
	v_or_b32_e32 v92, 32, v140
	v_cvt_pk_bf16_f32 v83, v88, v89
	v_pk_mul_f32 v[78:79], v[86:87], v[78:79] op_sel_hi:[0,1]
	v_mad_i64_i32 v[88:89], s[2:3], v92, s10, v[114:115]
	v_cvt_pk_bf16_f32 v84, v94, v95
	v_cvt_pk_bf16_f32 v85, v90, v91
	v_mul_f32_e32 v87, 0xbfb8aa3b, v78
	v_lshl_add_u64 v[88:89], v[88:89], 0, v[110:111]
	v_exp_f32_e32 v87, v87
	global_store_dwordx4 v[88:89], v[82:85], off
	v_pk_mul_f32 v[70:71], v[86:87], v[70:71] op_sel_hi:[0,1]
	s_nop 0
	v_mul_f32_e32 v83, 0xbfb8aa3b, v79
	v_exp_f32_e32 v83, v83
	v_add_f32_e32 v82, 1.0, v87
	v_pk_mul_f32 v[70:71], v[78:79], v[70:71]
	v_rcp_f32_e32 v82, v82
	v_add_f32_e32 v78, 1.0, v83
	v_rcp_f32_e32 v83, v78
	v_pk_mul_f32 v[78:79], v[86:87], v[80:81] op_sel_hi:[0,1]
	v_pk_mul_f32 v[74:75], v[86:87], v[74:75] op_sel_hi:[0,1]
	v_pk_mul_f32 v[72:73], v[86:87], v[72:73] op_sel_hi:[0,1]
	v_mul_f32_e32 v81, 0xbfb8aa3b, v79
	v_pk_mul_f32 v[70:71], v[82:83], v[70:71]
	v_mul_f32_e32 v82, 0xbfb8aa3b, v74
	v_pk_mul_f32 v[72:73], v[78:79], v[72:73]
	v_mul_f32_e32 v79, 0xbfb8aa3b, v75
	v_pk_mul_f32 v[66:67], v[86:87], v[66:67] op_sel_hi:[0,1]
	v_exp_f32_e32 v82, v82
	v_exp_f32_e32 v79, v79
	v_pk_mul_f32 v[66:67], v[74:75], v[66:67]
	v_pk_mul_f32 v[74:75], v[86:87], v[76:77] op_sel_hi:[0,1]
	v_mul_f32_e32 v76, 0xbfb8aa3b, v74
	v_mul_f32_e32 v77, 0xbfb8aa3b, v75
	v_exp_f32_e32 v76, v76
	v_exp_f32_e32 v77, v77
	v_mul_f32_e32 v80, 0xbfb8aa3b, v78
	v_add_f32_e32 v78, 1.0, v82
	v_add_f32_e32 v79, 1.0, v79
	v_exp_f32_e32 v80, v80
	v_exp_f32_e32 v81, v81
	v_rcp_f32_e32 v78, v78
	v_rcp_f32_e32 v79, v79
	v_add_f32_e32 v76, 1.0, v76
	v_add_f32_e32 v77, 1.0, v77
	v_rcp_f32_e32 v76, v76
	v_rcp_f32_e32 v77, v77
	v_add_f32_e32 v80, 1.0, v80
	v_add_f32_e32 v81, 1.0, v81
	v_pk_mul_f32 v[78:79], v[78:79], v[66:67]
	v_pk_mul_f32 v[66:67], v[86:87], v[68:69] op_sel_hi:[0,1]
	v_rcp_f32_e32 v80, v80
	v_rcp_f32_e32 v81, v81
	v_pk_mul_f32 v[66:67], v[74:75], v[66:67]
	v_fmamk_f32 v69, v152, 0x3a800000, v222
	v_pk_mul_f32 v[74:75], v[76:77], v[66:67]
	v_cvt_pk_bf16_f32 v66, v70, v71
	v_rsq_f32_e32 v70, v69
	v_pk_mul_f32 v[72:73], v[80:81], v[72:73]
	v_or_b32_e32 v76, 48, v140
	v_cvt_pk_bf16_f32 v67, v72, v73
	v_mad_i64_i32 v[72:73], s[2:3], v76, s10, v[114:115]
	v_pk_mul_f32 v[62:63], v[70:71], v[62:63] op_sel_hi:[0,1]
	v_cvt_pk_bf16_f32 v68, v78, v79
	v_cvt_pk_bf16_f32 v69, v74, v75
	v_mul_f32_e32 v71, 0xbfb8aa3b, v62
	v_lshl_add_u64 v[72:73], v[72:73], 0, v[110:111]
	v_exp_f32_e32 v71, v71
	global_store_dwordx4 v[72:73], v[66:69], off
	v_pk_mul_f32 v[54:55], v[70:71], v[54:55] op_sel_hi:[0,1]
	s_nop 0
	v_mul_f32_e32 v67, 0xbfb8aa3b, v63
	v_exp_f32_e32 v67, v67
	v_add_f32_e32 v66, 1.0, v71
	v_pk_mul_f32 v[54:55], v[62:63], v[54:55]
	v_rcp_f32_e32 v66, v66
	v_add_f32_e32 v62, 1.0, v67
	v_rcp_f32_e32 v67, v62
	v_pk_mul_f32 v[62:63], v[70:71], v[64:65] op_sel_hi:[0,1]
	v_pk_mul_f32 v[58:59], v[70:71], v[58:59] op_sel_hi:[0,1]
	v_pk_mul_f32 v[56:57], v[70:71], v[56:57] op_sel_hi:[0,1]
	v_mul_f32_e32 v65, 0xbfb8aa3b, v63
	v_pk_mul_f32 v[54:55], v[66:67], v[54:55]
	v_mul_f32_e32 v66, 0xbfb8aa3b, v58
	v_pk_mul_f32 v[56:57], v[62:63], v[56:57]
	v_mul_f32_e32 v63, 0xbfb8aa3b, v59
	v_pk_mul_f32 v[50:51], v[70:71], v[50:51] op_sel_hi:[0,1]
	v_exp_f32_e32 v66, v66
	v_exp_f32_e32 v63, v63
	v_pk_mul_f32 v[50:51], v[58:59], v[50:51]
	v_pk_mul_f32 v[58:59], v[70:71], v[60:61] op_sel_hi:[0,1]
	v_mul_f32_e32 v60, 0xbfb8aa3b, v58
	v_mul_f32_e32 v61, 0xbfb8aa3b, v59
	v_exp_f32_e32 v60, v60
	v_exp_f32_e32 v61, v61
	v_mul_f32_e32 v64, 0xbfb8aa3b, v62
	v_add_f32_e32 v62, 1.0, v66
	v_add_f32_e32 v63, 1.0, v63
	v_rcp_f32_e32 v62, v62
	v_rcp_f32_e32 v63, v63
	v_exp_f32_e32 v64, v64
	v_exp_f32_e32 v65, v65
	v_add_f32_e32 v60, 1.0, v60
	v_add_f32_e32 v61, 1.0, v61
	v_rcp_f32_e32 v60, v60
	v_rcp_f32_e32 v61, v61
	v_pk_mul_f32 v[62:63], v[62:63], v[50:51]
	v_pk_mul_f32 v[50:51], v[70:71], v[52:53] op_sel_hi:[0,1]
	v_add_f32_e32 v64, 1.0, v64
	v_add_f32_e32 v65, 1.0, v65
	v_pk_mul_f32 v[50:51], v[58:59], v[50:51]
	v_rcp_f32_e32 v64, v64
	v_rcp_f32_e32 v65, v65
	v_pk_mul_f32 v[58:59], v[60:61], v[50:51]
	v_fmamk_f32 v51, v153, 0x3a800000, v222
	v_cvt_pk_bf16_f32 v50, v54, v55
	v_rsq_f32_e32 v54, v51
	v_add_u32_e32 v68, 0x80, v140
	v_pk_mul_f32 v[56:57], v[64:65], v[56:57]
	v_cvt_pk_bf16_f32 v52, v62, v63
	v_cvt_pk_bf16_f32 v51, v56, v57
	v_pk_mul_f32 v[46:47], v[54:55], v[46:47] op_sel_hi:[0,1]
	v_mad_i64_i32 v[56:57], s[2:3], v68, s10, v[114:115]
	v_cvt_pk_bf16_f32 v53, v58, v59
	v_mul_f32_e32 v55, 0xbfb8aa3b, v46
	v_lshl_add_u64 v[56:57], v[56:57], 0, v[110:111]
	v_exp_f32_e32 v55, v55
	global_store_dwordx4 v[56:57], v[50:53], off
; __device__ __forceinline__ unsigned cvtpk(float lo, float hi) { f32x2 v = {lo, hi}; bf16x2_t b = __builtin_convertvector(v, bf16x2_t); return __builtin_bit_cast(unsigned, b); }
; #define PG8_BAR __builtin_amdgcn_s_barrier()
;     __device__ __forceinline__ void operator()(const f32x4 (&acc)[2][2][4][2], const Unit& u, int wr, int wc, int fr, int fq, const float (&pv)[8]) const {
;     ...
;             for (int m = 0; m < 4; ++m) { const int row = row0 + ai * HALF + m * 16; const float rs = __builtin_amdgcn_rsqf(pv[ai * 4 + m] * (1.f / DM) + EPS);
;                 float hv[8];
; #pragma unroll
;                 for (int n = 0; n < 2; ++n)
; #pragma unroll
;                     for (int j = 0; j < 4; ++j) { const float g = acc[ai][0][m][n][j] * rs, uu = acc[ai][1][m][n][j] * rs;
;                         const float e = __builtin_amdgcn_exp2f(-g * LOG2E); hv[n * 4 + j] = g * uu * __builtin_amdgcn_rcpf(1.f + e); }
;                 u32x4 w; w.x = cvtpk(hv[0], hv[1]); w.y = cvtpk(hv[2], hv[3]); w.z = cvtpk(hv[4], hv[5]); w.w = cvtpk(hv[6], hv[7]);
;                 *(u32x4*)(H + (size_t)row * DFF + col0) = w; }
; template <class Epi>
; __device__ __forceinline__ void gemm_phase(LAS unsigned char* lds, const Gemm g, const StaticOrder& S, const Epi& E, const int wave_id) {
;     ...
;         if (!has_next) break;
; #pragma unroll
;         for (int a = 0; a < 2; ++a)
; #pragma unroll
;             for (int b = 0; b < 2; ++b)
; #pragma unroll
;                 for (int m = 0; m < 4; ++m)
; #pragma unroll
;                     for (int n = 0; n < 2; ++n) acc[a][b][m][n] = (f32x4){0.f, 0.f, 0.f, 0.f};
;         cur = nxt; cA = nA; cB = nB; ++ui;
;         if (wr == 1) PG8_BAR;
;     }
	v_pk_mul_f32 v[38:39], v[54:55], v[38:39] op_sel_hi:[0,1]
	s_nop 0
	v_mul_f32_e32 v51, 0xbfb8aa3b, v47
	v_exp_f32_e32 v51, v51
	v_add_f32_e32 v50, 1.0, v55
	v_pk_mul_f32 v[38:39], v[46:47], v[38:39]
	v_rcp_f32_e32 v50, v50
	v_add_f32_e32 v46, 1.0, v51
	v_rcp_f32_e32 v51, v46
	v_pk_mul_f32 v[46:47], v[54:55], v[48:49] op_sel_hi:[0,1]
	v_pk_mul_f32 v[42:43], v[54:55], v[42:43] op_sel_hi:[0,1]
	v_pk_mul_f32 v[40:41], v[54:55], v[40:41] op_sel_hi:[0,1]
	v_mul_f32_e32 v49, 0xbfb8aa3b, v47
	v_pk_mul_f32 v[38:39], v[50:51], v[38:39]
	v_mul_f32_e32 v50, 0xbfb8aa3b, v42
	v_pk_mul_f32 v[40:41], v[46:47], v[40:41]
	v_mul_f32_e32 v47, 0xbfb8aa3b, v43
	v_pk_mul_f32 v[34:35], v[54:55], v[34:35] op_sel_hi:[0,1]
	v_exp_f32_e32 v50, v50
	v_exp_f32_e32 v47, v47
	v_pk_mul_f32 v[34:35], v[42:43], v[34:35]
	v_pk_mul_f32 v[42:43], v[54:55], v[44:45] op_sel_hi:[0,1]
	v_mul_f32_e32 v44, 0xbfb8aa3b, v42
	v_mul_f32_e32 v45, 0xbfb8aa3b, v43
	v_exp_f32_e32 v44, v44
	v_exp_f32_e32 v45, v45
	v_mul_f32_e32 v48, 0xbfb8aa3b, v46
	v_add_f32_e32 v46, 1.0, v50
	v_add_f32_e32 v47, 1.0, v47
	v_rcp_f32_e32 v46, v46
	v_rcp_f32_e32 v47, v47
	v_exp_f32_e32 v48, v48
	v_exp_f32_e32 v49, v49
	v_add_f32_e32 v44, 1.0, v44
	v_add_f32_e32 v45, 1.0, v45
	v_rcp_f32_e32 v44, v44
	v_rcp_f32_e32 v45, v45
	v_pk_mul_f32 v[46:47], v[46:47], v[34:35]
	v_pk_mul_f32 v[34:35], v[54:55], v[36:37] op_sel_hi:[0,1]
	v_add_f32_e32 v48, 1.0, v48
	v_add_f32_e32 v49, 1.0, v49
	v_pk_mul_f32 v[34:35], v[42:43], v[34:35]
	v_rcp_f32_e32 v48, v48
	v_rcp_f32_e32 v49, v49
	v_pk_mul_f32 v[42:43], v[44:45], v[34:35]
	v_fmamk_f32 v35, v154, 0x3a800000, v222
	v_cvt_pk_bf16_f32 v34, v38, v39
	v_rsq_f32_e32 v38, v35
	v_pk_mul_f32 v[40:41], v[48:49], v[40:41]
	v_add_u32_e32 v44, 0x90, v140
	v_cvt_pk_bf16_f32 v35, v40, v41
	v_pk_mul_f32 v[30:31], v[38:39], v[30:31] op_sel_hi:[0,1]
	v_mad_i64_i32 v[40:41], s[2:3], v44, s10, v[114:115]
	v_cvt_pk_bf16_f32 v36, v46, v47
	v_cvt_pk_bf16_f32 v37, v42, v43
	v_mul_f32_e32 v39, 0xbfb8aa3b, v30
	v_lshl_add_u64 v[40:41], v[40:41], 0, v[110:111]
	v_exp_f32_e32 v39, v39
	global_store_dwordx4 v[40:41], v[34:37], off
	v_pk_mul_f32 v[22:23], v[38:39], v[22:23] op_sel_hi:[0,1]
	s_nop 0
	v_mul_f32_e32 v35, 0xbfb8aa3b, v31
	v_exp_f32_e32 v35, v35
	v_add_f32_e32 v34, 1.0, v39
	v_pk_mul_f32 v[22:23], v[30:31], v[22:23]
	v_rcp_f32_e32 v34, v34
	v_add_f32_e32 v30, 1.0, v35
	v_rcp_f32_e32 v35, v30
	v_pk_mul_f32 v[30:31], v[38:39], v[32:33] op_sel_hi:[0,1]
	v_pk_mul_f32 v[26:27], v[38:39], v[26:27] op_sel_hi:[0,1]
	v_pk_mul_f32 v[24:25], v[38:39], v[24:25] op_sel_hi:[0,1]
	v_mul_f32_e32 v33, 0xbfb8aa3b, v31
	v_pk_mul_f32 v[22:23], v[34:35], v[22:23]
	v_mul_f32_e32 v34, 0xbfb8aa3b, v26
	v_pk_mul_f32 v[24:25], v[30:31], v[24:25]
	v_mul_f32_e32 v31, 0xbfb8aa3b, v27
	v_pk_mul_f32 v[18:19], v[38:39], v[18:19] op_sel_hi:[0,1]
	v_exp_f32_e32 v34, v34
	v_exp_f32_e32 v31, v31
	v_pk_mul_f32 v[18:19], v[26:27], v[18:19]
	v_pk_mul_f32 v[26:27], v[38:39], v[28:29] op_sel_hi:[0,1]
	v_mul_f32_e32 v28, 0xbfb8aa3b, v26
	v_mul_f32_e32 v29, 0xbfb8aa3b, v27
	v_exp_f32_e32 v28, v28
	v_exp_f32_e32 v29, v29
	v_mul_f32_e32 v32, 0xbfb8aa3b, v30
	v_add_f32_e32 v30, 1.0, v34
	v_add_f32_e32 v31, 1.0, v31
	v_rcp_f32_e32 v30, v30
	v_rcp_f32_e32 v31, v31
	v_exp_f32_e32 v32, v32
	v_exp_f32_e32 v33, v33
	v_add_f32_e32 v28, 1.0, v28
	v_add_f32_e32 v29, 1.0, v29
	v_rcp_f32_e32 v28, v28
	v_rcp_f32_e32 v29, v29
	v_pk_mul_f32 v[30:31], v[30:31], v[18:19]
	v_pk_mul_f32 v[18:19], v[38:39], v[20:21] op_sel_hi:[0,1]
	v_add_f32_e32 v32, 1.0, v32
	v_add_f32_e32 v33, 1.0, v33
	v_pk_mul_f32 v[18:19], v[26:27], v[18:19]
	v_rcp_f32_e32 v32, v32
	v_rcp_f32_e32 v33, v33
	v_pk_mul_f32 v[26:27], v[28:29], v[18:19]
	v_fmamk_f32 v19, v155, 0x3a800000, v222
	v_cvt_pk_bf16_f32 v18, v22, v23
	v_rsq_f32_e32 v22, v19
	v_pk_mul_f32 v[24:25], v[32:33], v[24:25]
	v_add_u32_e32 v28, 0xa0, v140
	v_cvt_pk_bf16_f32 v19, v24, v25
	v_pk_mul_f32 v[14:15], v[22:23], v[14:15] op_sel_hi:[0,1]
	v_mad_i64_i32 v[24:25], s[2:3], v28, s10, v[114:115]
	v_cvt_pk_bf16_f32 v20, v30, v31
	v_cvt_pk_bf16_f32 v21, v26, v27
	v_mul_f32_e32 v23, 0xbfb8aa3b, v14
	v_lshl_add_u64 v[24:25], v[24:25], 0, v[110:111]
	v_exp_f32_e32 v23, v23
	global_store_dwordx4 v[24:25], v[18:21], off
	v_pk_mul_f32 v[6:7], v[22:23], v[6:7] op_sel_hi:[0,1]
	s_nop 0
	v_mul_f32_e32 v19, 0xbfb8aa3b, v15
	v_exp_f32_e32 v19, v19
	v_add_f32_e32 v18, 1.0, v23
	v_pk_mul_f32 v[6:7], v[14:15], v[6:7]
	v_rcp_f32_e32 v18, v18
	v_add_f32_e32 v14, 1.0, v19
	v_rcp_f32_e32 v19, v14
	v_pk_mul_f32 v[14:15], v[22:23], v[16:17] op_sel_hi:[0,1]
	v_pk_mul_f32 v[10:11], v[22:23], v[10:11] op_sel_hi:[0,1]
	v_pk_mul_f32 v[8:9], v[22:23], v[8:9] op_sel_hi:[0,1]
	v_mul_f32_e32 v17, 0xbfb8aa3b, v15
	v_pk_mul_f32 v[6:7], v[18:19], v[6:7]
	v_mul_f32_e32 v18, 0xbfb8aa3b, v10
	v_pk_mul_f32 v[8:9], v[14:15], v[8:9]
	v_mul_f32_e32 v15, 0xbfb8aa3b, v11
	v_pk_mul_f32 v[2:3], v[22:23], v[2:3] op_sel_hi:[0,1]
	v_exp_f32_e32 v18, v18
	v_exp_f32_e32 v15, v15
	v_pk_mul_f32 v[2:3], v[10:11], v[2:3]
	v_pk_mul_f32 v[10:11], v[22:23], v[12:13] op_sel_hi:[0,1]
	v_mul_f32_e32 v12, 0xbfb8aa3b, v10
	v_mul_f32_e32 v13, 0xbfb8aa3b, v11
	v_mul_f32_e32 v16, 0xbfb8aa3b, v14
	v_exp_f32_e32 v12, v12
	v_exp_f32_e32 v13, v13
	v_exp_f32_e32 v16, v16
	v_exp_f32_e32 v17, v17
	v_add_f32_e32 v14, 1.0, v18
	v_add_f32_e32 v15, 1.0, v15
	v_rcp_f32_e32 v14, v14
	v_rcp_f32_e32 v15, v15
	v_add_f32_e32 v12, 1.0, v12
	v_add_f32_e32 v13, 1.0, v13
	v_add_f32_e32 v16, 1.0, v16
	v_add_f32_e32 v17, 1.0, v17
	v_rcp_f32_e32 v12, v12
	v_rcp_f32_e32 v13, v13
	v_rcp_f32_e32 v16, v16
	v_rcp_f32_e32 v17, v17
	v_pk_mul_f32 v[14:15], v[14:15], v[2:3]
	v_pk_mul_f32 v[2:3], v[22:23], v[4:5] op_sel_hi:[0,1]
	v_pk_mul_f32 v[2:3], v[10:11], v[2:3]
	v_pk_mul_f32 v[8:9], v[16:17], v[8:9]
	v_pk_mul_f32 v[10:11], v[12:13], v[2:3]
	v_add_u32_e32 v12, 0xb0, v140
	v_cvt_pk_bf16_f32 v2, v6, v7
	v_mad_i64_i32 v[6:7], s[2:3], v12, s10, v[114:115]
	v_cvt_pk_bf16_f32 v3, v8, v9
	v_cvt_pk_bf16_f32 v4, v14, v15
	v_cvt_pk_bf16_f32 v5, v10, v11
	v_lshl_add_u64 v[6:7], v[6:7], 0, v[110:111]
	s_mov_b64 s[2:3], -1
	global_store_dwordx4 v[6:7], v[2:5], off
	s_cbranch_vccnz .LBB0_142
	s_andn2_b64 vcc, exec, s[24:25]
	s_cbranch_vccnz .LBB0_141
	s_barrier
	s_branch .LBB0_141

; __device__ __forceinline__ unsigned cvtpk(float lo, float hi) { f32x2 v = {lo, hi}; bf16x2_t b = __builtin_convertvector(v, bf16x2_t); return __builtin_bit_cast(unsigned, b); }
;     __device__ __forceinline__ void operator()(const f32x4 (&acc)[2][2][4][2], const Unit& u, int wr, int wc, int fr, int fq, const float (&pv)[8]) const {
;         const int row0 = u.pm * BM + wr * 64 + fr, col0 = u.pn * BM + wc * 32 + 8 * fq;
;         const float sc = (u.pn >= t0 && u.pn < t1) ? tscale : 1.f;
; #pragma unroll
;         for (int ai = 0; ai < 2; ++ai)
; #pragma unroll
;             for (int m = 0; m < 4; ++m) { const int row = row0 + ai * HALF + m * 16; const float rs = __builtin_amdgcn_rsqf(pv[ai * 4 + m] * (1.f / DM) + EPS) * sc;
;                 bf16_t* rowp = O + (size_t)row * ldc + col0;
; #pragma unroll
;                 for (int bj = 0; bj < 2; ++bj) { const f32x4 v0 = acc[ai][bj][m][0] * rs, v1 = acc[ai][bj][m][1] * rs;
;                     u32x4 w; w.x = cvtpk(v0[0], v0[1]); w.y = cvtpk(v0[2], v0[3]); w.z = cvtpk(v1[0], v1[1]); w.w = cvtpk(v1[2], v1[3]);
;                     *(u32x4*)(rowp + bj * HALF) = w; } }
;     }
.LBB0_293:
	s_cmp_ge_i32 s48, s33
	s_waitcnt vmcnt(8)
	v_fmamk_f32 v141, v148, 0x3a800000, v222
	s_cselect_b64 s[2:3], -1, 0
	s_cmp_lt_i32 s48, s42
	v_rsq_f32_e32 v141, v141
	s_cselect_b64 s[10:11], -1, 0
	s_and_b64 vcc, s[2:3], s[10:11]
	v_lshl_or_b32 v142, s48, 8, v146
	v_cndmask_b32_e32 v157, 1.0, v228, vcc
	v_ashrrev_i32_e32 v143, 31, v142
	v_mul_f32_e32 v156, v157, v141
	v_mad_i64_i32 v[158:159], s[2:3], s44, v140, 0
	v_lshl_add_u64 v[158:159], v[158:159], 1, s[14:15]
	v_lshlrev_b64 v[142:143], 1, v[142:143]
	v_pk_mul_f32 v[128:129], v[156:157], v[128:129] op_sel_hi:[0,1]
	v_pk_mul_f32 v[126:127], v[156:157], v[126:127] op_sel_hi:[0,1]
	v_pk_mul_f32 v[160:161], v[156:157], v[124:125] op_sel_hi:[0,1]
	v_pk_mul_f32 v[124:125], v[156:157], v[122:123] op_sel_hi:[0,1]
	v_lshl_add_u64 v[158:159], v[158:159], 0, v[142:143]
	v_cvt_pk_bf16_f32 v122, v126, v127
	v_cvt_pk_bf16_f32 v123, v128, v129
	v_cvt_pk_bf16_f32 v124, v124, v125
	v_cvt_pk_bf16_f32 v125, v160, v161
	global_store_dwordx4 v[158:159], v[122:125], off
	v_pk_mul_f32 v[118:119], v[156:157], v[118:119] op_sel_hi:[0,1]
	v_pk_mul_f32 v[120:121], v[156:157], v[120:121] op_sel_hi:[0,1]
	v_pk_mul_f32 v[122:123], v[156:157], v[112:113] op_sel_hi:[0,1]
	v_pk_mul_f32 v[112:113], v[156:157], v[110:111] op_sel_hi:[0,1]
	v_cvt_pk_bf16_f32 v112, v112, v113
	v_fmamk_f32 v113, v149, 0x3a800000, v222
	v_cvt_pk_bf16_f32 v110, v118, v119
	v_rsq_f32_e32 v118, v113
	v_cvt_pk_bf16_f32 v111, v120, v121
	v_cvt_pk_bf16_f32 v113, v122, v123
	global_store_dwordx4 v[158:159], v[110:113], off offset:256
	s_andn2_b64 vcc, exec, s[40:41]
	s_nop 0
	v_or_b32_e32 v111, 16, v140
	v_mul_f32_e32 v110, v157, v118
	v_mad_i64_i32 v[112:113], s[2:3], s44, v111, 0
	v_lshl_add_u64 v[112:113], v[112:113], 1, s[14:15]
	v_pk_mul_f32 v[116:117], v[110:111], v[116:117] op_sel_hi:[0,1]
	v_pk_mul_f32 v[114:115], v[110:111], v[114:115] op_sel_hi:[0,1]
	v_pk_mul_f32 v[118:119], v[110:111], v[108:109] op_sel_hi:[0,1]
	v_pk_mul_f32 v[108:109], v[110:111], v[106:107] op_sel_hi:[0,1]
	v_lshl_add_u64 v[112:113], v[112:113], 0, v[142:143]
	v_cvt_pk_bf16_f32 v106, v114, v115
	v_cvt_pk_bf16_f32 v107, v116, v117
	v_cvt_pk_bf16_f32 v108, v108, v109
	v_cvt_pk_bf16_f32 v109, v118, v119
	global_store_dwordx4 v[112:113], v[106:109], off
	v_pk_mul_f32 v[102:103], v[110:111], v[102:103] op_sel_hi:[0,1]
	v_pk_mul_f32 v[104:105], v[110:111], v[104:105] op_sel_hi:[0,1]
	v_pk_mul_f32 v[106:107], v[110:111], v[96:97] op_sel_hi:[0,1]
	v_pk_mul_f32 v[96:97], v[110:111], v[94:95] op_sel_hi:[0,1]
	v_cvt_pk_bf16_f32 v96, v96, v97
	v_fmamk_f32 v97, v150, 0x3a800000, v222
	v_cvt_pk_bf16_f32 v94, v102, v103
	v_rsq_f32_e32 v102, v97
	v_cvt_pk_bf16_f32 v95, v104, v105
	v_cvt_pk_bf16_f32 v97, v106, v107
	global_store_dwordx4 v[112:113], v[94:97], off offset:256
	s_nop 1
	v_or_b32_e32 v95, 32, v140
	v_mul_f32_e32 v94, v157, v102
	v_mad_i64_i32 v[96:97], s[2:3], s44, v95, 0
	v_lshl_add_u64 v[96:97], v[96:97], 1, s[14:15]
	v_pk_mul_f32 v[100:101], v[94:95], v[100:101] op_sel_hi:[0,1]
	v_pk_mul_f32 v[98:99], v[94:95], v[98:99] op_sel_hi:[0,1]
	v_pk_mul_f32 v[102:103], v[94:95], v[92:93] op_sel_hi:[0,1]
	v_pk_mul_f32 v[92:93], v[94:95], v[90:91] op_sel_hi:[0,1]
	v_lshl_add_u64 v[96:97], v[96:97], 0, v[142:143]
	v_cvt_pk_bf16_f32 v90, v98, v99
	v_cvt_pk_bf16_f32 v91, v100, v101
	v_cvt_pk_bf16_f32 v92, v92, v93
	v_cvt_pk_bf16_f32 v93, v102, v103
	global_store_dwordx4 v[96:97], v[90:93], off
	v_pk_mul_f32 v[86:87], v[94:95], v[86:87] op_sel_hi:[0,1]
	v_pk_mul_f32 v[88:89], v[94:95], v[88:89] op_sel_hi:[0,1]
	v_pk_mul_f32 v[90:91], v[94:95], v[80:81] op_sel_hi:[0,1]
	v_pk_mul_f32 v[80:81], v[94:95], v[78:79] op_sel_hi:[0,1]
	v_cvt_pk_bf16_f32 v80, v80, v81
	v_fmamk_f32 v81, v151, 0x3a800000, v222
	v_cvt_pk_bf16_f32 v78, v86, v87
	v_rsq_f32_e32 v86, v81
	v_cvt_pk_bf16_f32 v79, v88, v89
	v_cvt_pk_bf16_f32 v81, v90, v91
	global_store_dwordx4 v[96:97], v[78:81], off offset:256
	s_nop 1
	v_or_b32_e32 v79, 48, v140
	v_mul_f32_e32 v78, v157, v86
	v_mad_i64_i32 v[80:81], s[2:3], s44, v79, 0
	v_lshl_add_u64 v[80:81], v[80:81], 1, s[14:15]
	v_pk_mul_f32 v[84:85], v[78:79], v[84:85] op_sel_hi:[0,1]
	v_pk_mul_f32 v[82:83], v[78:79], v[82:83] op_sel_hi:[0,1]
	v_pk_mul_f32 v[86:87], v[78:79], v[76:77] op_sel_hi:[0,1]
	v_pk_mul_f32 v[76:77], v[78:79], v[74:75] op_sel_hi:[0,1]
	v_lshl_add_u64 v[80:81], v[80:81], 0, v[142:143]
	v_cvt_pk_bf16_f32 v74, v82, v83
	v_cvt_pk_bf16_f32 v75, v84, v85
	v_cvt_pk_bf16_f32 v76, v76, v77
	v_cvt_pk_bf16_f32 v77, v86, v87
	global_store_dwordx4 v[80:81], v[74:77], off
	v_pk_mul_f32 v[70:71], v[78:79], v[70:71] op_sel_hi:[0,1]
	v_pk_mul_f32 v[72:73], v[78:79], v[72:73] op_sel_hi:[0,1]
	v_pk_mul_f32 v[74:75], v[78:79], v[68:69] op_sel_hi:[0,1]
	v_pk_mul_f32 v[68:69], v[78:79], v[66:67] op_sel_hi:[0,1]
; __device__ __forceinline__ unsigned cvtpk(float lo, float hi) { f32x2 v = {lo, hi}; bf16x2_t b = __builtin_convertvector(v, bf16x2_t); return __builtin_bit_cast(unsigned, b); }
; #define PG8_BAR __builtin_amdgcn_s_barrier()
;     __device__ __forceinline__ void operator()(const f32x4 (&acc)[2][2][4][2], const Unit& u, int wr, int wc, int fr, int fq, const float (&pv)[8]) const {
;     ...
;             for (int m = 0; m < 4; ++m) { const int row = row0 + ai * HALF + m * 16; const float rs = __builtin_amdgcn_rsqf(pv[ai * 4 + m] * (1.f / DM) + EPS) * sc;
;                 bf16_t* rowp = O + (size_t)row * ldc + col0;
; #pragma unroll
;                 for (int bj = 0; bj < 2; ++bj) { const f32x4 v0 = acc[ai][bj][m][0] * rs, v1 = acc[ai][bj][m][1] * rs;
;                     u32x4 w; w.x = cvtpk(v0[0], v0[1]); w.y = cvtpk(v0[2], v0[3]); w.z = cvtpk(v1[0], v1[1]); w.w = cvtpk(v1[2], v1[3]);
;                     *(u32x4*)(rowp + bj * HALF) = w; } }
;     }
; template <class Epi>
; __device__ __forceinline__ void gemm_phase(LAS unsigned char* lds, const Gemm g, const StaticOrder& S, const Epi& E, const int wave_id) {
;     ...
;         if (!has_next) break;
; #pragma unroll
;         for (int a = 0; a < 2; ++a)
; #pragma unroll
;             for (int b = 0; b < 2; ++b)
; #pragma unroll
;                 for (int m = 0; m < 4; ++m)
; #pragma unroll
;                     for (int n = 0; n < 2; ++n) acc[a][b][m][n] = (f32x4){0.f, 0.f, 0.f, 0.f};
;         cur = nxt; cA = nA; cB = nB; ++ui;
;         if (wr == 1) PG8_BAR;
;     }
	v_cvt_pk_bf16_f32 v68, v68, v69
	v_fmamk_f32 v69, v152, 0x3a800000, v222
	v_cvt_pk_bf16_f32 v66, v70, v71
	v_rsq_f32_e32 v70, v69
	v_cvt_pk_bf16_f32 v67, v72, v73
	v_cvt_pk_bf16_f32 v69, v74, v75
	global_store_dwordx4 v[80:81], v[66:69], off offset:256
	s_nop 1
	v_add_u32_e32 v67, 0x80, v140
	v_mul_f32_e32 v66, v157, v70
	v_mad_i64_i32 v[68:69], s[2:3], s44, v67, 0
	v_lshl_add_u64 v[68:69], v[68:69], 1, s[14:15]
	v_pk_mul_f32 v[64:65], v[66:67], v[64:65] op_sel_hi:[0,1]
	v_pk_mul_f32 v[62:63], v[66:67], v[62:63] op_sel_hi:[0,1]
	v_pk_mul_f32 v[70:71], v[66:67], v[60:61] op_sel_hi:[0,1]
	v_pk_mul_f32 v[60:61], v[66:67], v[58:59] op_sel_hi:[0,1]
	v_lshl_add_u64 v[68:69], v[68:69], 0, v[142:143]
	v_cvt_pk_bf16_f32 v58, v62, v63
	v_cvt_pk_bf16_f32 v59, v64, v65
	v_cvt_pk_bf16_f32 v60, v60, v61
	v_cvt_pk_bf16_f32 v61, v70, v71
	global_store_dwordx4 v[68:69], v[58:61], off
	v_pk_mul_f32 v[54:55], v[66:67], v[54:55] op_sel_hi:[0,1]
	v_pk_mul_f32 v[56:57], v[66:67], v[56:57] op_sel_hi:[0,1]
	v_pk_mul_f32 v[58:59], v[66:67], v[48:49] op_sel_hi:[0,1]
	v_pk_mul_f32 v[48:49], v[66:67], v[46:47] op_sel_hi:[0,1]
	v_cvt_pk_bf16_f32 v48, v48, v49
	v_fmamk_f32 v49, v153, 0x3a800000, v222
	v_cvt_pk_bf16_f32 v46, v54, v55
	v_rsq_f32_e32 v54, v49
	v_cvt_pk_bf16_f32 v47, v56, v57
	v_cvt_pk_bf16_f32 v49, v58, v59
	global_store_dwordx4 v[68:69], v[46:49], off offset:256
	s_nop 1
	v_add_u32_e32 v47, 0x90, v140
	v_mul_f32_e32 v46, v157, v54
	v_mad_i64_i32 v[48:49], s[2:3], s44, v47, 0
	v_lshl_add_u64 v[48:49], v[48:49], 1, s[14:15]
	v_pk_mul_f32 v[52:53], v[46:47], v[52:53] op_sel_hi:[0,1]
	v_pk_mul_f32 v[50:51], v[46:47], v[50:51] op_sel_hi:[0,1]
	v_pk_mul_f32 v[54:55], v[46:47], v[44:45] op_sel_hi:[0,1]
	v_pk_mul_f32 v[44:45], v[46:47], v[42:43] op_sel_hi:[0,1]
	v_lshl_add_u64 v[48:49], v[48:49], 0, v[142:143]
	v_cvt_pk_bf16_f32 v42, v50, v51
	v_cvt_pk_bf16_f32 v43, v52, v53
	v_cvt_pk_bf16_f32 v44, v44, v45
	v_cvt_pk_bf16_f32 v45, v54, v55
	global_store_dwordx4 v[48:49], v[42:45], off
	v_pk_mul_f32 v[38:39], v[46:47], v[38:39] op_sel_hi:[0,1]
	v_pk_mul_f32 v[40:41], v[46:47], v[40:41] op_sel_hi:[0,1]
	v_pk_mul_f32 v[42:43], v[46:47], v[32:33] op_sel_hi:[0,1]
	v_pk_mul_f32 v[32:33], v[46:47], v[30:31] op_sel_hi:[0,1]
	v_cvt_pk_bf16_f32 v32, v32, v33
	v_fmamk_f32 v33, v154, 0x3a800000, v222
	v_cvt_pk_bf16_f32 v30, v38, v39
	v_rsq_f32_e32 v38, v33
	v_cvt_pk_bf16_f32 v31, v40, v41
	v_cvt_pk_bf16_f32 v33, v42, v43
	global_store_dwordx4 v[48:49], v[30:33], off offset:256
	s_nop 1
	v_add_u32_e32 v31, 0xa0, v140
	v_mul_f32_e32 v30, v157, v38
	v_mad_i64_i32 v[32:33], s[2:3], s44, v31, 0
	v_lshl_add_u64 v[32:33], v[32:33], 1, s[14:15]
	v_pk_mul_f32 v[36:37], v[30:31], v[36:37] op_sel_hi:[0,1]
	v_pk_mul_f32 v[34:35], v[30:31], v[34:35] op_sel_hi:[0,1]
	v_pk_mul_f32 v[38:39], v[30:31], v[28:29] op_sel_hi:[0,1]
	v_pk_mul_f32 v[28:29], v[30:31], v[26:27] op_sel_hi:[0,1]
	v_lshl_add_u64 v[32:33], v[32:33], 0, v[142:143]
	v_cvt_pk_bf16_f32 v26, v34, v35
	v_cvt_pk_bf16_f32 v27, v36, v37
	v_cvt_pk_bf16_f32 v28, v28, v29
	v_cvt_pk_bf16_f32 v29, v38, v39
	global_store_dwordx4 v[32:33], v[26:29], off
	v_pk_mul_f32 v[22:23], v[30:31], v[22:23] op_sel_hi:[0,1]
	v_pk_mul_f32 v[24:25], v[30:31], v[24:25] op_sel_hi:[0,1]
	v_pk_mul_f32 v[26:27], v[30:31], v[16:17] op_sel_hi:[0,1]
	v_pk_mul_f32 v[16:17], v[30:31], v[14:15] op_sel_hi:[0,1]
	v_cvt_pk_bf16_f32 v16, v16, v17
	v_fmamk_f32 v17, v155, 0x3a800000, v222
	v_cvt_pk_bf16_f32 v14, v22, v23
	v_rsq_f32_e32 v22, v17
	v_cvt_pk_bf16_f32 v15, v24, v25
	v_cvt_pk_bf16_f32 v17, v26, v27
	global_store_dwordx4 v[32:33], v[14:17], off offset:256
	s_nop 1
	v_add_u32_e32 v15, 0xb0, v140
	v_mul_f32_e32 v14, v157, v22
	v_mad_i64_i32 v[16:17], s[2:3], s44, v15, 0
	v_lshl_add_u64 v[16:17], v[16:17], 1, s[14:15]
	v_pk_mul_f32 v[20:21], v[14:15], v[20:21] op_sel_hi:[0,1]
	v_pk_mul_f32 v[18:19], v[14:15], v[18:19] op_sel_hi:[0,1]
	v_pk_mul_f32 v[22:23], v[14:15], v[12:13] op_sel_hi:[0,1]
	v_pk_mul_f32 v[12:13], v[14:15], v[10:11] op_sel_hi:[0,1]
	v_lshl_add_u64 v[16:17], v[16:17], 0, v[142:143]
	v_cvt_pk_bf16_f32 v10, v18, v19
	v_cvt_pk_bf16_f32 v11, v20, v21
	v_cvt_pk_bf16_f32 v12, v12, v13
	v_cvt_pk_bf16_f32 v13, v22, v23
	global_store_dwordx4 v[16:17], v[10:13], off
	v_pk_mul_f32 v[8:9], v[14:15], v[8:9] op_sel_hi:[0,1]
	v_pk_mul_f32 v[6:7], v[14:15], v[6:7] op_sel_hi:[0,1]
	v_pk_mul_f32 v[10:11], v[14:15], v[4:5] op_sel_hi:[0,1]
	v_pk_mul_f32 v[4:5], v[14:15], v[2:3] op_sel_hi:[0,1]
	v_cvt_pk_bf16_f32 v2, v6, v7
	v_cvt_pk_bf16_f32 v3, v8, v9
	v_cvt_pk_bf16_f32 v4, v4, v5
	v_cvt_pk_bf16_f32 v5, v10, v11
	s_mov_b64 s[2:3], -1
	global_store_dwordx4 v[16:17], v[2:5], off offset:256
	s_cbranch_vccnz .LBB0_284
	s_andn2_b64 vcc, exec, s[18:19]
	s_cbranch_vccnz .LBB0_283
	s_barrier
	s_branch .LBB0_283

; __global__ void __launch_bounds__(NTHREADS) fwd_megakernel(Params P) {
;     ...
;         if (ph == 0) grid.sync(); else if (ph < 24) xcd_barrier(xbar);
.LBB0_415:
	v_readlane_b32 s2, v254, 62
	s_cmp_lg_u32 s2, 0
	s_mov_b64 s[0:1], -1
	s_cselect_b64 s[2:3], -1, 0
	s_andn2_b64 vcc, exec, s[2:3]
	s_mov_b64 s[2:3], 0
	s_branch .LBB0_402
